# grid barrier: pipelined polling of the arrival counter (three loads in flight) ahead of the one-load-per-round-trip spin
# speedup vs baseline: 1.0112x; 1.0030x over previous
.LBB0_447:
	s_or_b64 exec, exec, s[12:13]
	v_cvt_f32_u32_e32 v4, v2
	s_waitcnt vmcnt(0)
	v_readfirstlane_b32 s3, v3
	v_sub_u32_e32 v3, 0, v2
	v_rcp_iflag_f32_e32 v4, v4
	v_add_u32_e32 v5, s3, v1
	v_mul_f32_e32 v4, 0x4f7ffffe, v4
	v_cvt_u32_f32_e32 v4, v4
	v_mul_lo_u32 v1, v3, v4
	v_mul_hi_u32 v1, v4, v1
	v_add_u32_e32 v1, v4, v1
	v_mul_hi_u32 v1, v5, v1
	v_mul_lo_u32 v3, v1, v2
	v_sub_u32_e32 v3, v5, v3
	v_add_u32_e32 v4, 1, v1
	v_cmp_ge_u32_e32 vcc, v3, v2
	s_nop 1
	v_cndmask_b32_e32 v1, v1, v4, vcc
	v_sub_u32_e32 v4, v3, v2
	v_cndmask_b32_e32 v3, v3, v4, vcc
	v_add_u32_e32 v4, 1, v1
	v_cmp_ge_u32_e32 vcc, v3, v2
	v_add_u32_e32 v3, 1, v5
	s_nop 0
	v_cndmask_b32_e32 v1, v1, v4, vcc
	v_mul_lo_u32 v4, v2, v1
	v_add_u32_e32 v2, v4, v2
	v_cmp_ne_u32_e32 vcc, v3, v2
	s_and_saveexec_b64 s[10:11], vcc
	s_xor_b64 s[10:11], exec, s[10:11]
	s_cbranch_execz .LBB0_461
	s_waitcnt lgkmcnt(0)
	v_add_u32_e32 v1, 1, v1
	v_mul_lo_u32 v1, v1, v0
	s_add_u32 s14, s6, 0x3400
	s_addc_u32 s15, s7, 0
	global_load_dword v0, v145, s[14:15] sc1
	s_waitcnt vmcnt(0)
	v_cmp_lt_u32_e32 vcc, v0, v1
	s_and_saveexec_b64 s[12:13], vcc
	v_mov_b32_e32 v11, 0x800
	global_load_dword v8, v145, s[14:15] sc1
	s_sleep 6
	global_load_dword v9, v145, s[14:15] sc1
	s_sleep 6
.Lfp_loop_0:
	global_load_dword v10, v145, s[14:15] sc1
	s_waitcnt vmcnt(2)
	v_cmp_ge_u32_e32 vcc, v8, v1
	s_cbranch_vccnz .Lfp_done_0
	s_sleep 6
	global_load_dword v8, v145, s[14:15] sc1
	s_waitcnt vmcnt(2)
	v_cmp_ge_u32_e32 vcc, v9, v1
	s_cbranch_vccnz .Lfp_done_0
	s_sleep 6
	global_load_dword v9, v145, s[14:15] sc1
	s_waitcnt vmcnt(2)
	v_cmp_ge_u32_e32 vcc, v10, v1
	s_cbranch_vccnz .Lfp_done_0
	s_sleep 6
	v_subrev_u32_e32 v11, 1, v11
	v_cmp_ne_u32_e32 vcc, 0, v11
	s_cbranch_vccnz .Lfp_loop_0
	s_waitcnt vmcnt(0)
	s_branch .Lfp_slow_0
.Lfp_done_0:
	s_waitcnt vmcnt(0)
	s_branch .LBB0_460
.Lfp_slow_0:
	s_cbranch_execz .LBB0_460
	s_mov_b32 s3, 1
	s_mov_b64 s[16:17], 0
	s_branch .LBB0_451

.LBB0_464:
	s_or_b64 exec, exec, s[12:13]
	s_waitcnt vmcnt(0)
	v_readfirstlane_b32 s3, v2
	v_cvt_f32_u32_e32 v2, v0
	v_sub_u32_e32 v3, 0, v0
	v_add_u32_e32 v1, s3, v1
	s_add_u32 s10, s6, 0x3400
	v_rcp_iflag_f32_e32 v2, v2
	s_addc_u32 s11, s7, 0
	s_mov_b64 s[14:15], 0
	v_mul_f32_e32 v2, 0x4f7ffffe, v2
	v_cvt_u32_f32_e32 v2, v2
	v_mul_lo_u32 v3, v3, v2
	v_mul_hi_u32 v3, v2, v3
	v_add_u32_e32 v2, v2, v3
	v_mul_hi_u32 v2, v1, v2
	v_mul_lo_u32 v3, v2, v0
	v_sub_u32_e32 v3, v1, v3
	v_cmp_ge_u32_e32 vcc, v3, v0
	v_add_u32_e32 v4, 1, v2
	v_add_u32_e32 v1, 1, v1
	v_cndmask_b32_e32 v2, v2, v4, vcc
	v_sub_u32_e32 v4, v3, v0
	v_cndmask_b32_e32 v3, v3, v4, vcc
	v_cmp_ge_u32_e32 vcc, v3, v0
	v_add_u32_e32 v3, 1, v2
	s_nop 0
	v_cndmask_b32_e32 v2, v2, v3, vcc
	v_mul_lo_u32 v3, v0, v2
	v_add_u32_e32 v0, v3, v0
	v_cmp_ne_u32_e32 vcc, v1, v0
	v_mov_b32_e32 v2, v0
	v_mov_b64_e32 v[0:1], s[10:11]
	s_and_saveexec_b64 s[12:13], vcc
	s_cbranch_execz .LBB0_476
	global_load_dword v0, v145, s[10:11] sc1
	s_mov_b64 s[18:19], 0
	s_waitcnt vmcnt(0)
	v_cmp_lt_u32_e32 vcc, v0, v2
	s_and_saveexec_b64 s[16:17], vcc
	v_mov_b32_e32 v11, 0x800
	global_load_dword v8, v145, s[10:11] sc1
	s_sleep 6
	global_load_dword v9, v145, s[10:11] sc1
	s_sleep 6
.Lfp_loop_1:
	global_load_dword v10, v145, s[10:11] sc1
	s_waitcnt vmcnt(2)
	v_cmp_ge_u32_e32 vcc, v8, v2
	s_cbranch_vccnz .Lfp_done_1
	s_sleep 6
	global_load_dword v8, v145, s[10:11] sc1
	s_waitcnt vmcnt(2)
	v_cmp_ge_u32_e32 vcc, v9, v2
	s_cbranch_vccnz .Lfp_done_1
	s_sleep 6
	global_load_dword v9, v145, s[10:11] sc1
	s_waitcnt vmcnt(2)
	v_cmp_ge_u32_e32 vcc, v10, v2
	s_cbranch_vccnz .Lfp_done_1
	s_sleep 6
	v_subrev_u32_e32 v11, 1, v11
	v_cmp_ne_u32_e32 vcc, 0, v11
	s_cbranch_vccnz .Lfp_loop_1
	s_waitcnt vmcnt(0)
	s_branch .Lfp_slow_1

.Lfp_slow_1:
	s_cbranch_execz .LBB0_475
	s_add_u32 s14, s6, 0x200
	s_addc_u32 s15, s7, 0
	s_mov_b32 s3, 1
	s_mov_b64 s[6:7], 0
	s_branch .LBB0_468

.LBB0_1400:
	s_or_b64 exec, exec, s[14:15]
	v_cvt_f32_u32_e32 v4, v2
	s_waitcnt vmcnt(0)
	v_readfirstlane_b32 s3, v3
	v_sub_u32_e32 v3, 0, v2
	v_rcp_iflag_f32_e32 v4, v4
	v_add_u32_e32 v5, s3, v1
	v_mul_f32_e32 v4, 0x4f7ffffe, v4
	v_cvt_u32_f32_e32 v4, v4
	v_mul_lo_u32 v1, v3, v4
	v_mul_hi_u32 v1, v4, v1
	v_add_u32_e32 v1, v4, v1
	v_mul_hi_u32 v1, v5, v1
	v_mul_lo_u32 v3, v1, v2
	v_sub_u32_e32 v3, v5, v3
	v_add_u32_e32 v4, 1, v1
	v_cmp_ge_u32_e32 vcc, v3, v2
	s_nop 1
	v_cndmask_b32_e32 v1, v1, v4, vcc
	v_sub_u32_e32 v4, v3, v2
	v_cndmask_b32_e32 v3, v3, v4, vcc
	v_add_u32_e32 v4, 1, v1
	v_cmp_ge_u32_e32 vcc, v3, v2
	v_add_u32_e32 v3, 1, v5
	s_nop 0
	v_cndmask_b32_e32 v1, v1, v4, vcc
	v_mul_lo_u32 v4, v2, v1
	v_add_u32_e32 v2, v4, v2
	v_cmp_ne_u32_e32 vcc, v3, v2
	s_and_saveexec_b64 s[12:13], vcc
	s_xor_b64 s[12:13], exec, s[12:13]
	s_cbranch_execz .LBB0_1414
	s_waitcnt lgkmcnt(0)
	v_add_u32_e32 v1, 1, v1
	v_mul_lo_u32 v1, v1, v0
	s_add_u32 s16, s8, 0x3400
	s_addc_u32 s17, s9, 0
	global_load_dword v0, v145, s[16:17] sc1
	s_waitcnt vmcnt(0)
	v_cmp_lt_u32_e32 vcc, v0, v1
	s_and_saveexec_b64 s[14:15], vcc
	v_mov_b32_e32 v11, 0x800
	global_load_dword v8, v145, s[16:17] sc1
	s_sleep 6
	global_load_dword v9, v145, s[16:17] sc1
	s_sleep 6
.Lfp_loop_14:
	global_load_dword v10, v145, s[16:17] sc1
	s_waitcnt vmcnt(2)
	v_cmp_ge_u32_e32 vcc, v8, v1
	s_cbranch_vccnz .Lfp_done_14
	s_sleep 6
	global_load_dword v8, v145, s[16:17] sc1
	s_waitcnt vmcnt(2)
	v_cmp_ge_u32_e32 vcc, v9, v1
	s_cbranch_vccnz .Lfp_done_14
	s_sleep 6
	global_load_dword v9, v145, s[16:17] sc1
	s_waitcnt vmcnt(2)
	v_cmp_ge_u32_e32 vcc, v10, v1
	s_cbranch_vccnz .Lfp_done_14
	s_sleep 6
	v_subrev_u32_e32 v11, 1, v11
	v_cmp_ne_u32_e32 vcc, 0, v11
	s_cbranch_vccnz .Lfp_loop_14
	s_waitcnt vmcnt(0)
	s_branch .Lfp_slow_14

.Lfp_slow_14:
	s_cbranch_execz .LBB0_1413
	s_mov_b32 s3, 1
	s_mov_b64 s[18:19], 0
	s_branch .LBB0_1404

.LBB0_1417:
	s_or_b64 exec, exec, s[14:15]
	s_waitcnt vmcnt(0)
	v_readfirstlane_b32 s3, v2
	v_cvt_f32_u32_e32 v2, v0
	v_sub_u32_e32 v3, 0, v0
	v_add_u32_e32 v1, s3, v1
	s_add_u32 s12, s8, 0x3400
	v_rcp_iflag_f32_e32 v2, v2
	s_addc_u32 s13, s9, 0
	s_mov_b64 s[16:17], 0
	v_mul_f32_e32 v2, 0x4f7ffffe, v2
	v_cvt_u32_f32_e32 v2, v2
	v_mul_lo_u32 v3, v3, v2
	v_mul_hi_u32 v3, v2, v3
	v_add_u32_e32 v2, v2, v3
	v_mul_hi_u32 v2, v1, v2
	v_mul_lo_u32 v3, v2, v0
	v_sub_u32_e32 v3, v1, v3
	v_cmp_ge_u32_e32 vcc, v3, v0
	v_add_u32_e32 v4, 1, v2
	v_add_u32_e32 v1, 1, v1
	v_cndmask_b32_e32 v2, v2, v4, vcc
	v_sub_u32_e32 v4, v3, v0
	v_cndmask_b32_e32 v3, v3, v4, vcc
	v_cmp_ge_u32_e32 vcc, v3, v0
	v_add_u32_e32 v3, 1, v2
	s_nop 0
	v_cndmask_b32_e32 v2, v2, v3, vcc
	v_mul_lo_u32 v3, v0, v2
	v_add_u32_e32 v0, v3, v0
	v_cmp_ne_u32_e32 vcc, v1, v0
	v_mov_b32_e32 v2, v0
	v_mov_b64_e32 v[0:1], s[12:13]
	s_and_saveexec_b64 s[14:15], vcc
	s_cbranch_execz .LBB0_1429
	global_load_dword v0, v145, s[12:13] sc1
	s_mov_b64 s[20:21], 0
	s_waitcnt vmcnt(0)
	v_cmp_lt_u32_e32 vcc, v0, v2
	s_and_saveexec_b64 s[18:19], vcc
	v_mov_b32_e32 v11, 0x800
	global_load_dword v8, v145, s[12:13] sc1
	s_sleep 6
	global_load_dword v9, v145, s[12:13] sc1
	s_sleep 6
.Lfp_loop_15:
	global_load_dword v10, v145, s[12:13] sc1
	s_waitcnt vmcnt(2)
	v_cmp_ge_u32_e32 vcc, v8, v2
	s_cbranch_vccnz .Lfp_done_15
	s_sleep 6
	global_load_dword v8, v145, s[12:13] sc1
	s_waitcnt vmcnt(2)
	v_cmp_ge_u32_e32 vcc, v9, v2
	s_cbranch_vccnz .Lfp_done_15
	s_sleep 6
	global_load_dword v9, v145, s[12:13] sc1
	s_waitcnt vmcnt(2)
	v_cmp_ge_u32_e32 vcc, v10, v2
	s_cbranch_vccnz .Lfp_done_15
	s_sleep 6
	v_subrev_u32_e32 v11, 1, v11
	v_cmp_ne_u32_e32 vcc, 0, v11
	s_cbranch_vccnz .Lfp_loop_15
	s_waitcnt vmcnt(0)
	s_branch .Lfp_slow_15

.Lfp_slow_15:
	s_cbranch_execz .LBB0_1428
	s_add_u32 s16, s8, 0x200
	s_addc_u32 s17, s9, 0
	s_mov_b32 s3, 1
	s_mov_b64 s[8:9], 0
	s_branch .LBB0_1421
